# 40 more adjacent zero-move pairs in the conv epilogue merged into 64-bit moves where the DPP read distance is preserved
# baseline (speedup 1.0000x reference)
.LBB0_760:
	s_or_b64 exec, exec, s[48:49]
	v_lshl_or_b32 v192, s12, 7, v219
	v_ashrrev_i32_e32 v193, 31, v192
	v_lshlrev_b64 v[56:57], 2, v[192:193]
	s_waitcnt lgkmcnt(0)
	s_barrier
	v_lshl_add_u64 v[58:59], s[52:53], 0, v[56:57]
	v_lshl_add_u64 v[68:69], s[66:67], 0, v[56:57]
	v_lshl_add_u64 v[70:71], s[68:69], 0, v[56:57]
	v_lshl_add_u64 v[84:85], s[54:55], 0, v[56:57]
	global_load_dwordx4 v[64:67], v[58:59], off offset:16
	global_load_dwordx4 v[80:83], v[58:59], off
	global_load_dwordx4 v[60:63], v[68:69], off offset:16
	global_load_dwordx4 v[76:79], v[68:69], off
	s_nop 0
	global_load_dwordx4 v[56:59], v[70:71], off offset:16
	global_load_dwordx4 v[72:75], v[70:71], off
	s_nop 0
	global_load_dwordx4 v[68:71], v[84:85], off offset:16
	s_nop 0
	global_load_dwordx4 v[84:87], v[84:85], off
	v_cndmask_b32_e64 v152, 0, 1, s[50:51]
	v_mov_b32_e32 v213, v212
	v_mov_b32_e32 v205, v204
	v_mov_b32_e32 v201, v200
	v_mov_b32_e32 v195, v194
	v_mov_b32_e32 v156, 0
	v_cmp_ne_u32_e64 s[46:47], 1, v152
	s_andn2_b64 vcc, exec, s[50:51]
	v_mov_b64_e32 v[172:173], 0
	v_mov_b64_e32 v[174:175], 0
	s_cbranch_vccnz .LBB0_762
	ds_read_b128 v[172:175], v222
.LBB0_762:
	v_cndmask_b32_e64 v152, 0, 1, s[56:57]
	v_cmp_ne_u32_e64 s[48:49], 1, v152
	s_andn2_b64 vcc, exec, s[56:57]
	v_mov_b32_e32 v157, 0
	v_mov_b64_e32 v[158:159], 0
	s_cbranch_vccnz .LBB0_764
	ds_read_b128 v[156:159], v223 offset:1024
.LBB0_764:
	v_mov_b32_e32 v152, 0
	s_and_b64 vcc, exec, s[46:47]
	v_mov_b64_e32 v[168:169], 0
	v_mov_b64_e32 v[170:171], 0
	s_cbranch_vccnz .LBB0_766
	ds_read_b128 v[168:171], v222 offset:16
.LBB0_766:
	s_and_b64 vcc, exec, s[48:49]
	v_mov_b32_e32 v153, 0
	v_mov_b64_e32 v[154:155], 0
	s_cbranch_vccnz .LBB0_768
	ds_read_b128 v[152:155], v223 offset:1040
.LBB0_768:
	v_pk_mul_f32 v[210:211], v[148:149], v[208:209] op_sel_hi:[1,0]
	v_mov_b64_e32 v[148:149], 0
	s_waitcnt lgkmcnt(0)
	v_mov_b32_dpp v172, v164 row_shr:1 row_mask:0xf bank_mask:0xf
	v_mov_b32_dpp v173, v165 row_shr:1 row_mask:0xf bank_mask:0xf
	v_mov_b32_dpp v148, v210 row_ror:15 row_mask:0xf bank_mask:0xf
	v_mov_b32_dpp v149, v211 row_ror:15 row_mask:0xf bank_mask:0xf
	s_waitcnt vmcnt(0)
	v_pk_fma_f32 v[172:173], v[80:81], v[172:173], v[84:85]
	v_pk_mul_f32 v[206:207], v[150:151], v[208:209] op_sel_hi:[1,0]
	v_mov_b64_e32 v[150:151], 0
	v_mov_b32_dpp v174, v166 row_shr:1 row_mask:0xf bank_mask:0xf
	v_mov_b32_dpp v175, v167 row_shr:1 row_mask:0xf bank_mask:0xf
	v_mov_b32_dpp v148, v164 row_shl:1 row_mask:0xf bank_mask:0xf
	v_mov_b32_dpp v149, v165 row_shl:1 row_mask:0xf bank_mask:0xf
	v_pk_fma_f32 v[172:173], v[164:165], v[76:77], v[172:173]
	v_mov_b32_dpp v150, v206 row_ror:15 row_mask:0xf bank_mask:0xf
	v_mov_b32_dpp v151, v207 row_ror:15 row_mask:0xf bank_mask:0xf
	v_pk_fma_f32 v[174:175], v[82:83], v[174:175], v[86:87]
	v_pk_fma_f32 v[148:149], v[72:73], v[148:149], v[172:173]
	v_mov_b32_dpp v150, v166 row_shl:1 row_mask:0xf bank_mask:0xf
	v_mov_b32_dpp v151, v167 row_shl:1 row_mask:0xf bank_mask:0xf
	v_pk_fma_f32 v[174:175], v[166:167], v[78:79], v[174:175]
	v_pk_mul_f32 v[172:173], v[148:149], v[148:149]
	v_pk_fma_f32 v[150:151], v[74:75], v[150:151], v[174:175]
	v_pk_mul_f32 v[172:173], v[148:149], v[172:173]
	v_pk_mul_f32 v[174:175], v[150:151], v[150:151]
	v_pk_fma_f32 v[172:173], v[172:173], s[70:71], v[148:149] op_sel_hi:[1,0,1]
	v_pk_mul_f32 v[174:175], v[150:151], v[174:175]
	v_pk_mul_f32 v[172:173], v[172:173], s[72:73] op_sel_hi:[1,0]
	v_pk_fma_f32 v[174:175], v[174:175], s[70:71], v[150:151] op_sel_hi:[1,0,1]
	v_min_f32_e32 v172, 0x41e6d4ca, v172
	v_pk_mul_f32 v[174:175], v[174:175], s[72:73] op_sel_hi:[1,0]
	v_exp_f32_e32 v233, v172
	v_min_f32_e32 v172, 0x41e6d4ca, v173
	v_exp_f32_e32 v232, v172
	v_min_f32_e32 v172, 0x41e6d4ca, v174
	v_exp_f32_e32 v173, v172
	v_min_f32_e32 v172, 0x41e6d4ca, v175
	v_exp_f32_e32 v172, v172
	v_mov_b32_e32 v230, v212
	v_mov_b32_e32 v231, v212
	v_pk_mul_f32 v[146:147], v[146:147], v[230:231]
	v_pk_mul_f32 v[144:145], v[144:145], v[212:213]
	v_pk_mul_f32 v[138:139], v[138:139], v[230:231]
	v_pk_mul_f32 v[136:137], v[136:137], v[212:213]
	v_pk_add_f32 v[212:213], v[232:233], 1.0 op_sel_hi:[1,0]
	v_pk_add_f32 v[230:231], v[172:173], 1.0 op_sel_hi:[1,0]
	v_mul_f32_e32 v232, v213, v212
	v_mul_f32_e32 v233, v231, v230
	v_pk_mul_f32 v[174:175], v[140:141], v[208:209] op_sel_hi:[1,0]
	v_mul_f32_e32 v172, v232, v233
	v_rcp_f32_e32 v199, v172
	v_mov_b32_dpp v168, v160 row_shr:1 row_mask:0xf bank_mask:0xf
	v_mov_b32_dpp v169, v161 row_shr:1 row_mask:0xf bank_mask:0xf
	v_pk_fma_f32 v[168:169], v[64:65], v[168:169], v[68:69]
	v_mul_f32_e32 v140, v232, v199
	v_pk_mul_f32 v[230:231], v[230:231], v[140:141] op_sel_hi:[1,0]
	v_mov_b32_e32 v140, 0
	v_mov_b32_e32 v141, 0
	v_pk_mul_f32 v[172:173], v[142:143], v[208:209] op_sel_hi:[1,0]
	v_mov_b32_dpp v140, v174 row_ror:15 row_mask:0xf bank_mask:0xf
	v_mov_b32_dpp v141, v175 row_ror:15 row_mask:0xf bank_mask:0xf
	v_mov_b64_e32 v[142:143], 0
	v_mov_b32_dpp v170, v162 row_shr:1 row_mask:0xf bank_mask:0xf
	v_mov_b32_dpp v171, v163 row_shr:1 row_mask:0xf bank_mask:0xf
	v_mov_b32_dpp v140, v160 row_shl:1 row_mask:0xf bank_mask:0xf
	v_mov_b32_dpp v141, v161 row_shl:1 row_mask:0xf bank_mask:0xf
	v_pk_fma_f32 v[168:169], v[160:161], v[60:61], v[168:169]
	v_mov_b32_dpp v142, v172 row_ror:15 row_mask:0xf bank_mask:0xf
	v_mov_b32_dpp v143, v173 row_ror:15 row_mask:0xf bank_mask:0xf
	v_pk_fma_f32 v[170:171], v[66:67], v[170:171], v[70:71]
	v_pk_fma_f32 v[140:141], v[56:57], v[140:141], v[168:169]
	v_mov_b32_dpp v142, v162 row_shl:1 row_mask:0xf bank_mask:0xf
	v_mov_b32_dpp v143, v163 row_shl:1 row_mask:0xf bank_mask:0xf
	v_pk_fma_f32 v[170:171], v[162:163], v[62:63], v[170:171]
	v_pk_mul_f32 v[168:169], v[140:141], v[140:141]
	v_pk_fma_f32 v[142:143], v[58:59], v[142:143], v[170:171]
	v_pk_mul_f32 v[168:169], v[140:141], v[168:169]
	v_pk_mul_f32 v[170:171], v[142:143], v[142:143]
	v_pk_fma_f32 v[168:169], v[168:169], s[70:71], v[140:141] op_sel_hi:[1,0,1]
	v_pk_mul_f32 v[170:171], v[142:143], v[170:171]
	v_pk_mul_f32 v[168:169], v[168:169], s[72:73] op_sel_hi:[1,0]
	v_pk_fma_f32 v[170:171], v[170:171], s[70:71], v[142:143] op_sel_hi:[1,0,1]
	v_min_f32_e32 v168, 0x41e6d4ca, v168
	v_mul_f32_e32 v234, v233, v199
	v_pk_mul_f32 v[170:171], v[170:171], s[72:73] op_sel_hi:[1,0]
	v_exp_f32_e32 v233, v168
	v_min_f32_e32 v168, 0x41e6d4ca, v169
	v_exp_f32_e32 v232, v168
	v_min_f32_e32 v168, 0x41e6d4ca, v170
	v_exp_f32_e32 v169, v168
	v_min_f32_e32 v168, 0x41e6d4ca, v171
	v_exp_f32_e32 v168, v168
	v_pk_mul_f32 v[170:171], v[212:213], v[234:235] op_sel_hi:[1,0]
	v_pk_add_f32 v[212:213], v[232:233], 1.0 op_sel_hi:[1,0]
	v_pk_mul_f32 v[170:171], v[148:149], v[170:171]
	v_pk_add_f32 v[168:169], v[168:169], 1.0 op_sel_hi:[1,0]
	v_mov_b32_e32 v232, v213
	v_mov_b32_e32 v233, v169
	v_mov_b32_e32 v234, v212
	v_mov_b32_e32 v235, v168
	v_pk_mul_f32 v[232:233], v[232:233], v[234:235]
	v_pk_mul_f32 v[170:171], v[144:145], v[170:171]
	v_mul_f32_e32 v199, v232, v233
	v_rcp_f32_e32 v199, v199
	v_add_u32_e32 v197, s11, v217
	v_pk_mul_f32 v[230:231], v[150:151], v[230:231]
	s_lshl_b32 s12, s10, 1
	v_mul_f32_e32 v234, v233, v199
	v_mul_f32_e32 v232, v232, v199
	v_pk_mul_f32 v[212:213], v[212:213], v[234:235] op_sel_hi:[1,0]
	v_pk_mul_f32 v[168:169], v[168:169], v[232:233] op_sel_hi:[1,0]
	v_pk_mul_f32 v[212:213], v[140:141], v[212:213]
	v_pk_mul_f32 v[168:169], v[142:143], v[168:169]
	v_pk_mul_f32 v[212:213], v[136:137], v[212:213]
	v_pk_mul_f32 v[232:233], v[138:139], v[168:169]
	v_cvt_pk_bf16_f32 v168, v170, v171
	v_cvt_pk_bf16_f32 v170, v212, v213
	v_mov_b64_e32 v[212:213], s[86:87]
	s_mul_i32 s15, s10, 0x10800
	v_pk_mul_f32 v[230:231], v[146:147], v[230:231]
	v_mad_i64_i32 v[212:213], s[10:11], v197, s90, v[212:213]
	s_mul_hi_i32 s16, s12, 0x8400
	v_cvt_pk_bf16_f32 v169, v230, v231
	v_cvt_pk_bf16_f32 v171, v232, v233
	v_lshl_add_u64 v[212:213], v[192:193], 1, v[212:213]
	global_store_dwordx4 v[212:213], v[168:171], off
	s_and_saveexec_b64 s[10:11], s[40:41]
	s_cbranch_execz .LBB0_770
	s_add_u32 s24, s4, s15
	s_addc_u32 s25, s5, s16
	v_lshl_add_u64 v[168:169], v[192:193], 2, s[24:25]
	global_store_dwordx4 v[168:169], v[148:151], off
	s_nop 1
	v_add_co_u32_e32 v148, vcc, 0x2000, v168
	s_nop 1
	v_addc_co_u32_e32 v149, vcc, 0, v169, vcc
	v_add_co_u32_e32 v150, vcc, 0x5000, v168
	global_store_dwordx4 v[148:149], v[164:167], off offset:3072
	s_nop 0
	v_addc_co_u32_e32 v151, vcc, 0, v169, vcc
	global_store_dwordx4 v[150:151], v[144:147], off offset:2048
	global_store_dwordx4 v[168:169], v[140:143], off offset:16
	global_store_dwordx4 v[148:149], v[160:163], off offset:3088
	global_store_dwordx4 v[150:151], v[136:139], off offset:2064
.LBB0_770:
	s_or_b64 exec, exec, s[10:11]
	v_mov_b32_e32 v209, v208
	v_pk_mul_f32 v[140:141], v[116:117], v[208:209]
	v_pk_mul_f32 v[116:117], v[120:121], v[202:203] op_sel_hi:[1,0]
	v_mov_b32_e32 v120, v204
	v_mov_b32_e32 v121, v204
	v_pk_mul_f32 v[102:103], v[102:103], v[120:121]
	v_pk_mul_f32 v[98:99], v[98:99], v[120:121]
	v_mov_b32_e32 v120, 0
	v_mov_b32_e32 v121, 0
	v_mov_b32_e32 v136, v208
	v_mov_b32_e32 v137, v208
	v_mov_b32_dpp v120, v164 row_ror:1 row_mask:0xf bank_mask:0xf
	v_mov_b32_dpp v121, v165 row_ror:1 row_mask:0xf bank_mask:0xf
	v_pk_mul_f32 v[138:139], v[118:119], v[136:137]
	v_pk_mul_f32 v[136:137], v[114:115], v[136:137]
	v_pk_mul_f32 v[118:119], v[126:127], v[202:203] op_sel_hi:[1,0]
	v_pk_mul_f32 v[124:125], v[124:125], v[202:203] op_sel_hi:[1,0]
	v_pk_mul_f32 v[114:115], v[122:123], v[202:203] op_sel_hi:[1,0]
	v_mov_b64_e32 v[122:123], 0
	v_mov_b64_e32 v[126:127], 0
	v_mov_b32_dpp v120, v210 row_shr:1 row_mask:0xf bank_mask:0xf
	v_mov_b32_dpp v121, v211 row_shr:1 row_mask:0xf bank_mask:0xf
	v_mov_b32_dpp v122, v166 row_ror:1 row_mask:0xf bank_mask:0xf
	v_mov_b32_dpp v123, v167 row_ror:1 row_mask:0xf bank_mask:0xf
	v_mov_b32_dpp v126, v124 row_ror:15 row_mask:0xf bank_mask:0xf
	v_mov_b32_dpp v127, v125 row_ror:15 row_mask:0xf bank_mask:0xf
	v_pk_fma_f32 v[120:121], v[80:81], v[120:121], v[84:85]
	v_mov_b64_e32 v[142:143], 0
	v_mov_b32_dpp v122, v206 row_shr:1 row_mask:0xf bank_mask:0xf
	v_mov_b32_dpp v123, v207 row_shr:1 row_mask:0xf bank_mask:0xf
	v_mov_b32_dpp v126, v210 row_shl:1 row_mask:0xf bank_mask:0xf
	v_mov_b32_dpp v127, v211 row_shl:1 row_mask:0xf bank_mask:0xf
	v_pk_fma_f32 v[120:121], v[210:211], v[76:77], v[120:121]
	v_mov_b32_dpp v142, v118 row_ror:15 row_mask:0xf bank_mask:0xf
	v_mov_b32_dpp v143, v119 row_ror:15 row_mask:0xf bank_mask:0xf
	v_pk_fma_f32 v[122:123], v[82:83], v[122:123], v[86:87]
	v_pk_fma_f32 v[120:121], v[72:73], v[126:127], v[120:121]
	v_mov_b32_dpp v142, v206 row_shl:1 row_mask:0xf bank_mask:0xf
	v_mov_b32_dpp v143, v207 row_shl:1 row_mask:0xf bank_mask:0xf
	v_pk_fma_f32 v[122:123], v[206:207], v[78:79], v[122:123]
	v_pk_mul_f32 v[126:127], v[120:121], v[120:121]
	v_pk_fma_f32 v[122:123], v[74:75], v[142:143], v[122:123]
	v_pk_mul_f32 v[126:127], v[120:121], v[126:127]
	v_pk_mul_f32 v[142:143], v[122:123], v[122:123]
	v_pk_fma_f32 v[126:127], v[126:127], s[70:71], v[120:121] op_sel_hi:[1,0,1]
	v_pk_mul_f32 v[142:143], v[122:123], v[142:143]
	v_pk_mul_f32 v[126:127], v[126:127], s[72:73] op_sel_hi:[1,0]
	v_pk_fma_f32 v[142:143], v[142:143], s[70:71], v[122:123] op_sel_hi:[1,0,1]
	v_min_f32_e32 v126, 0x41e6d4ca, v126
	v_pk_mul_f32 v[142:143], v[142:143], s[72:73] op_sel_hi:[1,0]
	v_exp_f32_e32 v145, v126
	v_min_f32_e32 v126, 0x41e6d4ca, v127
	v_exp_f32_e32 v144, v126
	v_min_f32_e32 v126, 0x41e6d4ca, v142
	v_exp_f32_e32 v127, v126
	v_min_f32_e32 v126, 0x41e6d4ca, v143
	v_exp_f32_e32 v126, v126
	v_pk_add_f32 v[142:143], v[144:145], 1.0 op_sel_hi:[1,0]
	v_pk_mul_f32 v[112:113], v[112:113], v[208:209]
	v_pk_add_f32 v[126:127], v[126:127], 1.0 op_sel_hi:[1,0]
	v_mul_f32_e32 v144, v143, v142
	v_mul_f32_e32 v145, v127, v126
	v_or_b32_e32 v148, 16, v197
	v_mul_f32_e32 v146, v144, v145
	v_rcp_f32_e32 v147, v146
	v_pk_mul_f32 v[108:109], v[108:109], v[202:203] op_sel_hi:[1,0]
	v_pk_mul_f32 v[110:111], v[110:111], v[202:203] op_sel_hi:[1,0]
	v_pk_mul_f32 v[106:107], v[106:107], v[202:203] op_sel_hi:[1,0]
	v_mul_f32_e32 v144, v144, v147
	v_mul_f32_e32 v146, v145, v147
	v_pk_mul_f32 v[126:127], v[126:127], v[144:145] op_sel_hi:[1,0]
	v_pk_mul_f32 v[142:143], v[142:143], v[146:147] op_sel_hi:[1,0]
	v_pk_mul_f32 v[122:123], v[122:123], v[126:127]
	v_mov_b32_e32 v126, 0
	v_mov_b32_e32 v127, 0
	v_pk_mul_f32 v[120:121], v[120:121], v[142:143]
	v_mov_b32_dpp v126, v160 row_ror:1 row_mask:0xf bank_mask:0xf
	v_mov_b32_dpp v127, v161 row_ror:1 row_mask:0xf bank_mask:0xf
	v_pk_mul_f32 v[122:123], v[138:139], v[122:123]
	v_pk_mul_f32 v[120:121], v[140:141], v[120:121]
	v_mov_b64_e32 v[138:139], 0
	v_mov_b64_e32 v[140:141], 0
	v_mov_b32_dpp v126, v174 row_shr:1 row_mask:0xf bank_mask:0xf
	v_mov_b32_dpp v127, v175 row_shr:1 row_mask:0xf bank_mask:0xf
	v_mov_b32_dpp v138, v162 row_ror:1 row_mask:0xf bank_mask:0xf
	v_mov_b32_dpp v139, v163 row_ror:1 row_mask:0xf bank_mask:0xf
	v_mov_b32_dpp v140, v116 row_ror:15 row_mask:0xf bank_mask:0xf
	v_mov_b32_dpp v141, v117 row_ror:15 row_mask:0xf bank_mask:0xf
	v_pk_fma_f32 v[126:127], v[64:65], v[126:127], v[68:69]
	v_mov_b64_e32 v[142:143], 0
	v_mov_b32_dpp v138, v172 row_shr:1 row_mask:0xf bank_mask:0xf
	v_mov_b32_dpp v139, v173 row_shr:1 row_mask:0xf bank_mask:0xf
	v_mov_b32_dpp v140, v174 row_shl:1 row_mask:0xf bank_mask:0xf
	v_mov_b32_dpp v141, v175 row_shl:1 row_mask:0xf bank_mask:0xf
	v_pk_fma_f32 v[126:127], v[174:175], v[60:61], v[126:127]
	v_mov_b32_dpp v142, v114 row_ror:15 row_mask:0xf bank_mask:0xf
	v_mov_b32_dpp v143, v115 row_ror:15 row_mask:0xf bank_mask:0xf
	v_pk_fma_f32 v[138:139], v[66:67], v[138:139], v[70:71]
	v_pk_fma_f32 v[126:127], v[56:57], v[140:141], v[126:127]
	v_mov_b32_dpp v142, v172 row_shl:1 row_mask:0xf bank_mask:0xf
	v_mov_b32_dpp v143, v173 row_shl:1 row_mask:0xf bank_mask:0xf
	v_pk_fma_f32 v[138:139], v[172:173], v[62:63], v[138:139]
	v_pk_mul_f32 v[140:141], v[126:127], v[126:127]
	v_pk_fma_f32 v[138:139], v[58:59], v[142:143], v[138:139]
	v_pk_mul_f32 v[140:141], v[126:127], v[140:141]
	v_pk_mul_f32 v[142:143], v[138:139], v[138:139]
	v_pk_fma_f32 v[140:141], v[140:141], s[70:71], v[126:127] op_sel_hi:[1,0,1]
	v_pk_mul_f32 v[142:143], v[138:139], v[142:143]
	v_pk_mul_f32 v[140:141], v[140:141], s[72:73] op_sel_hi:[1,0]
	v_pk_fma_f32 v[142:143], v[142:143], s[70:71], v[138:139] op_sel_hi:[1,0,1]
	v_min_f32_e32 v140, 0x41e6d4ca, v140
	v_pk_mul_f32 v[142:143], v[142:143], s[72:73] op_sel_hi:[1,0]
	v_exp_f32_e32 v145, v140
	v_min_f32_e32 v140, 0x41e6d4ca, v141
	v_exp_f32_e32 v144, v140
	v_min_f32_e32 v140, 0x41e6d4ca, v142
	v_exp_f32_e32 v141, v140
	v_min_f32_e32 v140, 0x41e6d4ca, v143
	v_exp_f32_e32 v140, v140
	v_pk_add_f32 v[142:143], v[144:145], 1.0 op_sel_hi:[1,0]
	v_pk_mul_f32 v[104:105], v[104:105], v[202:203] op_sel_hi:[1,0]
	v_pk_add_f32 v[140:141], v[140:141], 1.0 op_sel_hi:[1,0]
	v_mul_f32_e32 v144, v143, v142
	v_mul_f32_e32 v145, v141, v140
	v_mov_b32_dpp v156, v132 row_shl:1 row_mask:0xf bank_mask:0xf
	v_mul_f32_e32 v146, v144, v145
	v_rcp_f32_e32 v147, v146
	v_mov_b32_dpp v157, v133 row_shl:1 row_mask:0xf bank_mask:0xf
	v_mov_b32_dpp v158, v134 row_shl:1 row_mask:0xf bank_mask:0xf
	v_mov_b32_dpp v159, v135 row_shl:1 row_mask:0xf bank_mask:0xf
	v_mul_f32_e32 v146, v145, v147
	v_mul_f32_e32 v144, v144, v147
	v_pk_mul_f32 v[140:141], v[140:141], v[144:145] op_sel_hi:[1,0]
	v_pk_mul_f32 v[142:143], v[142:143], v[146:147] op_sel_hi:[1,0]
	v_pk_mul_f32 v[138:139], v[138:139], v[140:141]
	v_pk_mul_f32 v[126:127], v[126:127], v[142:143]
	v_pk_mul_f32 v[140:141], v[136:137], v[138:139]
	v_pk_mul_f32 v[112:113], v[112:113], v[126:127]
	v_cvt_pk_bf16_f32 v136, v120, v121
	v_mov_b64_e32 v[120:121], s[86:87]
	v_cvt_pk_bf16_f32 v137, v122, v123
	v_cvt_pk_bf16_f32 v138, v112, v113
	v_mad_i64_i32 v[122:123], s[10:11], v148, s90, v[120:121]
	v_lshlrev_b64 v[112:113], 1, v[192:193]
	v_cvt_pk_bf16_f32 v139, v140, v141
	v_lshl_add_u64 v[122:123], v[122:123], 0, v[112:113]
	global_store_dwordx4 v[122:123], v[136:139], off
	v_mov_b32_e32 v122, 0
	v_mov_b32_e32 v123, 0
	v_mov_b32_e32 v126, 0
	v_mov_b32_dpp v122, v210 row_ror:1 row_mask:0xf bank_mask:0xf
	v_mov_b32_dpp v123, v211 row_ror:1 row_mask:0xf bank_mask:0xf
	v_mov_b32_e32 v127, 0
	v_mov_b64_e32 v[136:137], 0
	v_mov_b32_dpp v122, v124 row_shr:1 row_mask:0xf bank_mask:0xf
	v_mov_b32_dpp v123, v125 row_shr:1 row_mask:0xf bank_mask:0xf
	v_mov_b32_dpp v126, v206 row_ror:1 row_mask:0xf bank_mask:0xf
	v_mov_b32_dpp v127, v207 row_ror:1 row_mask:0xf bank_mask:0xf
	v_mov_b32_dpp v136, v132 row_ror:15 row_mask:0xf bank_mask:0xf
	v_mov_b32_dpp v137, v133 row_ror:15 row_mask:0xf bank_mask:0xf
	v_pk_fma_f32 v[122:123], v[80:81], v[122:123], v[84:85]
	v_mov_b64_e32 v[138:139], 0
	v_mov_b32_dpp v126, v118 row_shr:1 row_mask:0xf bank_mask:0xf
	v_mov_b32_dpp v127, v119 row_shr:1 row_mask:0xf bank_mask:0xf
	v_mov_b32_dpp v136, v124 row_shl:1 row_mask:0xf bank_mask:0xf
	v_mov_b32_dpp v137, v125 row_shl:1 row_mask:0xf bank_mask:0xf
	v_pk_fma_f32 v[122:123], v[124:125], v[76:77], v[122:123]
	v_mov_b32_dpp v138, v134 row_ror:15 row_mask:0xf bank_mask:0xf
	v_mov_b32_dpp v139, v135 row_ror:15 row_mask:0xf bank_mask:0xf
	v_pk_fma_f32 v[126:127], v[82:83], v[126:127], v[86:87]
	v_pk_fma_f32 v[122:123], v[72:73], v[136:137], v[122:123]
	v_mov_b32_dpp v138, v118 row_shl:1 row_mask:0xf bank_mask:0xf
	v_mov_b32_dpp v139, v119 row_shl:1 row_mask:0xf bank_mask:0xf
	v_pk_fma_f32 v[126:127], v[118:119], v[78:79], v[126:127]
	v_pk_mul_f32 v[136:137], v[122:123], v[122:123]
	v_pk_fma_f32 v[126:127], v[74:75], v[138:139], v[126:127]
	v_pk_mul_f32 v[136:137], v[122:123], v[136:137]
	v_pk_mul_f32 v[138:139], v[126:127], v[126:127]
	v_pk_fma_f32 v[136:137], v[136:137], s[70:71], v[122:123] op_sel_hi:[1,0,1]
	v_pk_mul_f32 v[138:139], v[126:127], v[138:139]
	v_pk_mul_f32 v[136:137], v[136:137], s[72:73] op_sel_hi:[1,0]
	v_pk_fma_f32 v[138:139], v[138:139], s[70:71], v[126:127] op_sel_hi:[1,0,1]
	v_min_f32_e32 v136, 0x41e6d4ca, v136
	v_pk_mul_f32 v[138:139], v[138:139], s[72:73] op_sel_hi:[1,0]
	v_exp_f32_e32 v141, v136
	v_min_f32_e32 v136, 0x41e6d4ca, v137
	v_exp_f32_e32 v140, v136
	v_min_f32_e32 v136, 0x41e6d4ca, v138
	v_exp_f32_e32 v137, v136
	v_min_f32_e32 v136, 0x41e6d4ca, v139
	v_exp_f32_e32 v136, v136
	v_pk_add_f32 v[138:139], v[140:141], 1.0 op_sel_hi:[1,0]
	v_or_b32_e32 v144, 32, v197
	v_pk_add_f32 v[136:137], v[136:137], 1.0 op_sel_hi:[1,0]
	v_mul_f32_e32 v140, v139, v138
	v_mul_f32_e32 v141, v137, v136
	v_pk_mul_f32 v[100:101], v[100:101], v[204:205]
	v_mul_f32_e32 v142, v140, v141
	v_rcp_f32_e32 v143, v142
	v_mov_b32_dpp v152, v128 row_shl:1 row_mask:0xf bank_mask:0xf
	v_mov_b32_dpp v153, v129 row_shl:1 row_mask:0xf bank_mask:0xf
	v_mov_b32_dpp v154, v130 row_shl:1 row_mask:0xf bank_mask:0xf
	v_mul_f32_e32 v142, v141, v143
	v_pk_mul_f32 v[138:139], v[138:139], v[142:143] op_sel_hi:[1,0]
	v_mul_f32_e32 v140, v140, v143
	v_pk_mul_f32 v[122:123], v[122:123], v[138:139]
	v_pk_mul_f32 v[136:137], v[136:137], v[140:141] op_sel_hi:[1,0]
	v_pk_mul_f32 v[108:109], v[108:109], v[122:123]
	v_mov_b32_e32 v122, 0
	v_mov_b32_e32 v123, 0
	v_pk_mul_f32 v[126:127], v[126:127], v[136:137]
	v_mov_b32_dpp v122, v174 row_ror:1 row_mask:0xf bank_mask:0xf
	v_mov_b32_dpp v123, v175 row_ror:1 row_mask:0xf bank_mask:0xf
	v_pk_mul_f32 v[110:111], v[110:111], v[126:127]
	v_mov_b64_e32 v[126:127], 0
	v_mov_b64_e32 v[136:137], 0
	v_mov_b32_dpp v122, v116 row_shr:1 row_mask:0xf bank_mask:0xf
	v_mov_b32_dpp v123, v117 row_shr:1 row_mask:0xf bank_mask:0xf
	v_mov_b32_dpp v126, v172 row_ror:1 row_mask:0xf bank_mask:0xf
	v_mov_b32_dpp v127, v173 row_ror:1 row_mask:0xf bank_mask:0xf
	v_mov_b32_dpp v136, v128 row_ror:15 row_mask:0xf bank_mask:0xf
	v_mov_b32_dpp v137, v129 row_ror:15 row_mask:0xf bank_mask:0xf
	v_pk_fma_f32 v[122:123], v[64:65], v[122:123], v[68:69]
	v_mov_b64_e32 v[138:139], 0
	v_mov_b32_dpp v126, v114 row_shr:1 row_mask:0xf bank_mask:0xf
	v_mov_b32_dpp v127, v115 row_shr:1 row_mask:0xf bank_mask:0xf
	v_mov_b32_dpp v136, v116 row_shl:1 row_mask:0xf bank_mask:0xf
	v_mov_b32_dpp v137, v117 row_shl:1 row_mask:0xf bank_mask:0xf
	v_pk_fma_f32 v[122:123], v[116:117], v[60:61], v[122:123]
	v_mov_b32_dpp v138, v130 row_ror:15 row_mask:0xf bank_mask:0xf
	v_mov_b32_dpp v139, v131 row_ror:15 row_mask:0xf bank_mask:0xf
	v_pk_fma_f32 v[126:127], v[66:67], v[126:127], v[70:71]
	v_pk_fma_f32 v[122:123], v[56:57], v[136:137], v[122:123]
	v_mov_b32_dpp v138, v114 row_shl:1 row_mask:0xf bank_mask:0xf
	v_mov_b32_dpp v139, v115 row_shl:1 row_mask:0xf bank_mask:0xf
	v_pk_fma_f32 v[126:127], v[114:115], v[62:63], v[126:127]
	v_pk_mul_f32 v[136:137], v[122:123], v[122:123]
	v_pk_fma_f32 v[126:127], v[58:59], v[138:139], v[126:127]
	v_pk_mul_f32 v[136:137], v[122:123], v[136:137]
	v_pk_mul_f32 v[138:139], v[126:127], v[126:127]
	v_pk_fma_f32 v[136:137], v[136:137], s[70:71], v[122:123] op_sel_hi:[1,0,1]
	v_pk_mul_f32 v[138:139], v[126:127], v[138:139]
	v_pk_mul_f32 v[136:137], v[136:137], s[72:73] op_sel_hi:[1,0]
	v_pk_fma_f32 v[138:139], v[138:139], s[70:71], v[126:127] op_sel_hi:[1,0,1]
	v_min_f32_e32 v136, 0x41e6d4ca, v136
	v_pk_mul_f32 v[138:139], v[138:139], s[72:73] op_sel_hi:[1,0]
	v_exp_f32_e32 v141, v136
	v_min_f32_e32 v136, 0x41e6d4ca, v137
	v_exp_f32_e32 v140, v136
	v_min_f32_e32 v136, 0x41e6d4ca, v138
	v_exp_f32_e32 v137, v136
	v_min_f32_e32 v136, 0x41e6d4ca, v139
	v_exp_f32_e32 v136, v136
	v_pk_add_f32 v[138:139], v[140:141], 1.0 op_sel_hi:[1,0]
	v_mov_b32_dpp v155, v131 row_shl:1 row_mask:0xf bank_mask:0xf
	v_pk_add_f32 v[136:137], v[136:137], 1.0 op_sel_hi:[1,0]
	v_mul_f32_e32 v140, v139, v138
	v_mul_f32_e32 v141, v137, v136
	v_pk_mul_f32 v[96:97], v[96:97], v[204:205]
	v_mul_f32_e32 v142, v140, v141
	v_rcp_f32_e32 v143, v142
	s_or_b32 s14, s12, 1
	s_mul_hi_i32 s12, s14, 0x8400
	s_mul_i32 s14, s14, 0x8400
	v_mul_f32_e32 v142, v141, v143
	v_mul_f32_e32 v140, v140, v143
	v_pk_mul_f32 v[136:137], v[136:137], v[140:141] op_sel_hi:[1,0]
	v_pk_mul_f32 v[138:139], v[138:139], v[142:143] op_sel_hi:[1,0]
	v_pk_mul_f32 v[126:127], v[126:127], v[136:137]
	v_pk_mul_f32 v[122:123], v[122:123], v[138:139]
	v_pk_mul_f32 v[126:127], v[106:107], v[126:127]
	v_pk_mul_f32 v[106:107], v[104:105], v[122:123]
	v_cvt_pk_bf16_f32 v104, v108, v109
	v_mad_i64_i32 v[108:109], s[10:11], v144, s90, v[120:121]
	v_cvt_pk_bf16_f32 v105, v110, v111
	v_cvt_pk_bf16_f32 v106, v106, v107
	v_cvt_pk_bf16_f32 v107, v126, v127
	v_lshl_add_u64 v[108:109], v[108:109], 0, v[112:113]
	global_store_dwordx4 v[108:109], v[104:107], off
	v_or_b32_e32 v136, 48, v197
	s_nop 0
	v_mov_b32_e32 v104, 0
	v_mov_b32_e32 v105, 0
	v_mov_b32_e32 v106, 0
	v_mov_b32_dpp v104, v124 row_ror:1 row_mask:0xf bank_mask:0xf
	v_mov_b32_dpp v105, v125 row_ror:1 row_mask:0xf bank_mask:0xf
	v_mov_b32_e32 v107, 0
	v_mov_b32_dpp v104, v132 row_shr:1 row_mask:0xf bank_mask:0xf
	v_mov_b32_dpp v105, v133 row_shr:1 row_mask:0xf bank_mask:0xf
	v_mov_b32_dpp v106, v118 row_ror:1 row_mask:0xf bank_mask:0xf
	v_mov_b32_dpp v107, v119 row_ror:1 row_mask:0xf bank_mask:0xf
	v_pk_fma_f32 v[104:105], v[80:81], v[104:105], v[84:85]
	v_mov_b32_dpp v106, v134 row_shr:1 row_mask:0xf bank_mask:0xf
	v_mov_b32_dpp v107, v135 row_shr:1 row_mask:0xf bank_mask:0xf
	v_pk_fma_f32 v[104:105], v[132:133], v[76:77], v[104:105]
	v_pk_fma_f32 v[106:107], v[82:83], v[106:107], v[86:87]
	v_pk_fma_f32 v[104:105], v[72:73], v[156:157], v[104:105]
	v_pk_fma_f32 v[106:107], v[134:135], v[78:79], v[106:107]
	v_pk_mul_f32 v[108:109], v[104:105], v[104:105]
	v_pk_fma_f32 v[106:107], v[74:75], v[158:159], v[106:107]
	v_pk_mul_f32 v[108:109], v[104:105], v[108:109]
	v_pk_mul_f32 v[110:111], v[106:107], v[106:107]
	v_pk_fma_f32 v[108:109], v[108:109], s[70:71], v[104:105] op_sel_hi:[1,0,1]
	v_pk_mul_f32 v[110:111], v[106:107], v[110:111]
	v_pk_mul_f32 v[108:109], v[108:109], s[72:73] op_sel_hi:[1,0]
	v_pk_fma_f32 v[110:111], v[110:111], s[70:71], v[106:107] op_sel_hi:[1,0,1]
	v_min_f32_e32 v108, 0x41e6d4ca, v108
	v_pk_mul_f32 v[110:111], v[110:111], s[72:73] op_sel_hi:[1,0]
	v_exp_f32_e32 v119, v108
	v_min_f32_e32 v108, 0x41e6d4ca, v109
	v_exp_f32_e32 v118, v108
	v_min_f32_e32 v108, 0x41e6d4ca, v110
	v_exp_f32_e32 v109, v108
	v_min_f32_e32 v108, 0x41e6d4ca, v111
	v_exp_f32_e32 v108, v108
	v_pk_add_f32 v[110:111], v[118:119], 1.0 op_sel_hi:[1,0]
	v_pk_add_f32 v[108:109], v[108:109], 1.0 op_sel_hi:[1,0]
	v_mul_f32_e32 v118, v111, v110
	v_mul_f32_e32 v119, v109, v108
	s_nop 0
	v_mul_f32_e32 v122, v118, v119
	v_rcp_f32_e32 v123, v122
	s_nop 0
	v_mul_f32_e32 v118, v118, v123
	v_pk_mul_f32 v[108:109], v[108:109], v[118:119] op_sel_hi:[1,0]
	v_mul_f32_e32 v122, v119, v123
	v_pk_mul_f32 v[108:109], v[106:107], v[108:109]
	v_pk_mul_f32 v[110:111], v[110:111], v[122:123] op_sel_hi:[1,0]
	v_pk_mul_f32 v[118:119], v[102:103], v[108:109]
	v_mov_b32_e32 v108, 0
	v_mov_b32_e32 v109, 0
	v_pk_mul_f32 v[110:111], v[104:105], v[110:111]
	v_mov_b32_dpp v108, v116 row_ror:1 row_mask:0xf bank_mask:0xf
	v_mov_b32_dpp v109, v117 row_ror:1 row_mask:0xf bank_mask:0xf
	v_pk_mul_f32 v[122:123], v[100:101], v[110:111]
	v_mov_b32_e32 v110, 0
	v_mov_b32_e32 v111, 0
	v_mov_b32_dpp v108, v128 row_shr:1 row_mask:0xf bank_mask:0xf
	v_mov_b32_dpp v109, v129 row_shr:1 row_mask:0xf bank_mask:0xf
	v_mov_b32_dpp v110, v114 row_ror:1 row_mask:0xf bank_mask:0xf
	v_mov_b32_dpp v111, v115 row_ror:1 row_mask:0xf bank_mask:0xf
	v_pk_fma_f32 v[108:109], v[64:65], v[108:109], v[68:69]
	v_mov_b32_dpp v110, v130 row_shr:1 row_mask:0xf bank_mask:0xf
	v_mov_b32_dpp v111, v131 row_shr:1 row_mask:0xf bank_mask:0xf
	v_pk_fma_f32 v[108:109], v[128:129], v[60:61], v[108:109]
	v_pk_fma_f32 v[110:111], v[66:67], v[110:111], v[70:71]
	v_pk_fma_f32 v[108:109], v[56:57], v[152:153], v[108:109]
	v_pk_fma_f32 v[110:111], v[130:131], v[62:63], v[110:111]
	v_pk_mul_f32 v[114:115], v[108:109], v[108:109]
	v_pk_fma_f32 v[110:111], v[58:59], v[154:155], v[110:111]
	v_pk_mul_f32 v[114:115], v[108:109], v[114:115]
	v_pk_mul_f32 v[116:117], v[110:111], v[110:111]
	v_pk_fma_f32 v[114:115], v[114:115], s[70:71], v[108:109] op_sel_hi:[1,0,1]
	v_pk_mul_f32 v[116:117], v[110:111], v[116:117]
	v_pk_mul_f32 v[114:115], v[114:115], s[72:73] op_sel_hi:[1,0]
	v_pk_fma_f32 v[116:117], v[116:117], s[70:71], v[110:111] op_sel_hi:[1,0,1]
	v_min_f32_e32 v114, 0x41e6d4ca, v114
	v_pk_mul_f32 v[116:117], v[116:117], s[72:73] op_sel_hi:[1,0]
	v_exp_f32_e32 v125, v114
	v_min_f32_e32 v114, 0x41e6d4ca, v115
	v_exp_f32_e32 v124, v114
	v_min_f32_e32 v114, 0x41e6d4ca, v116
	v_exp_f32_e32 v115, v114
	v_min_f32_e32 v114, 0x41e6d4ca, v117
	v_exp_f32_e32 v114, v114
	v_pk_add_f32 v[116:117], v[124:125], 1.0 op_sel_hi:[1,0]
	v_pk_add_f32 v[114:115], v[114:115], 1.0 op_sel_hi:[1,0]
	v_mul_f32_e32 v124, v117, v116
	v_mul_f32_e32 v125, v115, v114
	s_nop 0
	v_mul_f32_e32 v126, v124, v125
	v_rcp_f32_e32 v127, v126
	s_nop 0
	v_mul_f32_e32 v126, v125, v127
	v_mul_f32_e32 v124, v124, v127
	v_pk_mul_f32 v[114:115], v[114:115], v[124:125] op_sel_hi:[1,0]
	v_pk_mul_f32 v[116:117], v[116:117], v[126:127] op_sel_hi:[1,0]
	v_pk_mul_f32 v[114:115], v[110:111], v[114:115]
	v_pk_mul_f32 v[116:117], v[108:109], v[116:117]
	v_pk_mul_f32 v[124:125], v[98:99], v[114:115]
	v_pk_mul_f32 v[116:117], v[96:97], v[116:117]
	v_cvt_pk_bf16_f32 v115, v118, v119
	v_mad_i64_i32 v[118:119], s[10:11], v136, s90, v[120:121]
	v_cvt_pk_bf16_f32 v114, v122, v123
	v_cvt_pk_bf16_f32 v116, v116, v117
	v_cvt_pk_bf16_f32 v117, v124, v125
	v_lshl_add_u64 v[118:119], v[118:119], 0, v[112:113]
	global_store_dwordx4 v[118:119], v[114:117], off
	s_and_saveexec_b64 s[10:11], s[58:59]
	s_cbranch_execz .LBB0_772
	s_add_u32 s24, s4, s14
	s_addc_u32 s25, s5, s12
	v_lshl_add_u64 v[114:115], v[192:193], 2, s[24:25]
	global_store_dwordx4 v[114:115], v[104:107], off
	s_nop 1
	v_add_co_u32_e32 v104, vcc, 0x2000, v114
	s_nop 1
	v_addc_co_u32_e32 v105, vcc, 0, v115, vcc
	v_add_co_u32_e32 v106, vcc, 0x5000, v114
	global_store_dwordx4 v[104:105], v[132:135], off offset:3072
	s_nop 0
	v_addc_co_u32_e32 v107, vcc, 0, v115, vcc
	global_store_dwordx4 v[106:107], v[100:103], off offset:2048
	global_store_dwordx4 v[114:115], v[108:111], off offset:16
	global_store_dwordx4 v[104:105], v[128:131], off offset:3088
	global_store_dwordx4 v[106:107], v[96:99], off offset:2064
.LBB0_772:
	s_or_b64 exec, exec, s[10:11]
	s_nop 0
	v_cndmask_b32_e64 v96, 0, 1, s[60:61]
	v_mov_b32_e32 v100, 0
	v_cmp_ne_u32_e64 s[46:47], 1, v96
	s_andn2_b64 vcc, exec, s[60:61]
	v_mov_b64_e32 v[108:109], 0
	v_mov_b64_e32 v[110:111], 0
	s_cbranch_vccnz .LBB0_774
	ds_read_b128 v[108:111], v224
.LBB0_774:
	v_cndmask_b32_e64 v96, 0, 1, s[62:63]
	v_cmp_ne_u32_e64 s[48:49], 1, v96
	s_andn2_b64 vcc, exec, s[62:63]
	v_mov_b32_e32 v101, 0
	v_mov_b64_e32 v[102:103], 0
	s_cbranch_vccnz .LBB0_776
	ds_read_b128 v[100:103], v225 offset:1024
.LBB0_776:
	v_mov_b32_e32 v96, 0
	s_and_b64 vcc, exec, s[46:47]
	v_mov_b64_e32 v[104:105], 0
	v_mov_b64_e32 v[106:107], 0
	s_cbranch_vccnz .LBB0_778
	ds_read_b128 v[104:107], v224 offset:16
.LBB0_778:
	s_and_b64 vcc, exec, s[48:49]
	v_mov_b32_e32 v97, 0
	v_mov_b64_e32 v[98:99], 0
	s_cbranch_vccnz .LBB0_780
	ds_read_b128 v[96:99], v225 offset:1040
.LBB0_780:
	v_pk_mul_f32 v[116:117], v[52:53], v[198:199] op_sel_hi:[1,0]
	v_mov_b64_e32 v[52:53], 0
	s_waitcnt lgkmcnt(0)
	v_mov_b32_dpp v108, v92 row_shr:1 row_mask:0xf bank_mask:0xf
	v_mov_b32_dpp v109, v93 row_shr:1 row_mask:0xf bank_mask:0xf
	v_mov_b32_dpp v52, v116 row_ror:15 row_mask:0xf bank_mask:0xf
	v_mov_b32_dpp v53, v117 row_ror:15 row_mask:0xf bank_mask:0xf
	v_pk_fma_f32 v[108:109], v[80:81], v[108:109], v[84:85]
	v_pk_mul_f32 v[114:115], v[54:55], v[198:199] op_sel_hi:[1,0]
	v_mov_b64_e32 v[54:55], 0
	v_mov_b32_dpp v110, v94 row_shr:1 row_mask:0xf bank_mask:0xf
	v_mov_b32_dpp v111, v95 row_shr:1 row_mask:0xf bank_mask:0xf
	v_mov_b32_dpp v52, v92 row_shl:1 row_mask:0xf bank_mask:0xf
	v_mov_b32_dpp v53, v93 row_shl:1 row_mask:0xf bank_mask:0xf
	v_pk_fma_f32 v[108:109], v[92:93], v[76:77], v[108:109]
	v_mov_b32_dpp v54, v114 row_ror:15 row_mask:0xf bank_mask:0xf
	v_mov_b32_dpp v55, v115 row_ror:15 row_mask:0xf bank_mask:0xf
	v_pk_fma_f32 v[110:111], v[82:83], v[110:111], v[86:87]
	v_pk_fma_f32 v[52:53], v[72:73], v[52:53], v[108:109]
	v_mov_b32_dpp v54, v94 row_shl:1 row_mask:0xf bank_mask:0xf
	v_mov_b32_dpp v55, v95 row_shl:1 row_mask:0xf bank_mask:0xf
	v_pk_fma_f32 v[110:111], v[94:95], v[78:79], v[110:111]
	v_pk_mul_f32 v[108:109], v[52:53], v[52:53]
	v_pk_fma_f32 v[54:55], v[74:75], v[54:55], v[110:111]
	v_pk_mul_f32 v[108:109], v[52:53], v[108:109]
	v_pk_mul_f32 v[110:111], v[54:55], v[54:55]
	v_pk_fma_f32 v[108:109], v[108:109], s[70:71], v[52:53] op_sel_hi:[1,0,1]
	v_pk_mul_f32 v[110:111], v[54:55], v[110:111]
	v_pk_mul_f32 v[108:109], v[108:109], s[72:73] op_sel_hi:[1,0]
	v_pk_fma_f32 v[110:111], v[110:111], s[70:71], v[54:55] op_sel_hi:[1,0,1]
	v_min_f32_e32 v108, 0x41e6d4ca, v108
	v_pk_mul_f32 v[110:111], v[110:111], s[72:73] op_sel_hi:[1,0]
	v_exp_f32_e32 v121, v108
	v_min_f32_e32 v108, 0x41e6d4ca, v109
	v_exp_f32_e32 v120, v108
	v_min_f32_e32 v108, 0x41e6d4ca, v110
	v_exp_f32_e32 v109, v108
	v_min_f32_e32 v108, 0x41e6d4ca, v111
	v_exp_f32_e32 v108, v108
	v_mov_b32_e32 v118, v200
	v_mov_b32_e32 v119, v200
	v_pk_mul_f32 v[50:51], v[50:51], v[118:119]
	v_pk_mul_f32 v[42:43], v[42:43], v[118:119]
	v_pk_add_f32 v[118:119], v[120:121], 1.0 op_sel_hi:[1,0]
	v_pk_add_f32 v[120:121], v[108:109], 1.0 op_sel_hi:[1,0]
	v_mul_f32_e32 v122, v119, v118
	v_mul_f32_e32 v123, v121, v120
	v_pk_mul_f32 v[110:111], v[44:45], v[198:199] op_sel_hi:[1,0]
	v_mul_f32_e32 v108, v122, v123
	v_rcp_f32_e32 v125, v108
	v_mov_b32_dpp v104, v88 row_shr:1 row_mask:0xf bank_mask:0xf
	v_mov_b32_dpp v105, v89 row_shr:1 row_mask:0xf bank_mask:0xf
	v_pk_fma_f32 v[104:105], v[64:65], v[104:105], v[68:69]
	v_mul_f32_e32 v44, v122, v125
	v_pk_mul_f32 v[120:121], v[120:121], v[44:45] op_sel_hi:[1,0]
	v_mov_b32_e32 v44, 0
	v_mov_b32_e32 v45, 0
	v_pk_mul_f32 v[108:109], v[46:47], v[198:199] op_sel_hi:[1,0]
	v_mov_b32_dpp v44, v110 row_ror:15 row_mask:0xf bank_mask:0xf
	v_mov_b32_dpp v45, v111 row_ror:15 row_mask:0xf bank_mask:0xf
	v_mov_b64_e32 v[46:47], 0
	v_mov_b32_dpp v106, v90 row_shr:1 row_mask:0xf bank_mask:0xf
	v_mov_b32_dpp v107, v91 row_shr:1 row_mask:0xf bank_mask:0xf
	v_mov_b32_dpp v44, v88 row_shl:1 row_mask:0xf bank_mask:0xf
	v_mov_b32_dpp v45, v89 row_shl:1 row_mask:0xf bank_mask:0xf
	v_pk_fma_f32 v[104:105], v[88:89], v[60:61], v[104:105]
	v_mov_b32_dpp v46, v108 row_ror:15 row_mask:0xf bank_mask:0xf
	v_mov_b32_dpp v47, v109 row_ror:15 row_mask:0xf bank_mask:0xf
	v_pk_fma_f32 v[106:107], v[66:67], v[106:107], v[70:71]
	v_pk_fma_f32 v[44:45], v[56:57], v[44:45], v[104:105]
	v_mov_b32_dpp v46, v90 row_shl:1 row_mask:0xf bank_mask:0xf
	v_mov_b32_dpp v47, v91 row_shl:1 row_mask:0xf bank_mask:0xf
	v_pk_fma_f32 v[106:107], v[90:91], v[62:63], v[106:107]
	v_pk_mul_f32 v[104:105], v[44:45], v[44:45]
	v_pk_fma_f32 v[46:47], v[58:59], v[46:47], v[106:107]
	v_pk_mul_f32 v[104:105], v[44:45], v[104:105]
	v_pk_mul_f32 v[106:107], v[46:47], v[46:47]
	v_pk_fma_f32 v[104:105], v[104:105], s[70:71], v[44:45] op_sel_hi:[1,0,1]
	v_pk_mul_f32 v[106:107], v[46:47], v[106:107]
	v_pk_mul_f32 v[104:105], v[104:105], s[72:73] op_sel_hi:[1,0]
	v_pk_fma_f32 v[106:107], v[106:107], s[70:71], v[46:47] op_sel_hi:[1,0,1]
	v_min_f32_e32 v104, 0x41e6d4ca, v104
	v_mul_f32_e32 v124, v123, v125
	v_pk_mul_f32 v[106:107], v[106:107], s[72:73] op_sel_hi:[1,0]
	v_exp_f32_e32 v123, v104
	v_min_f32_e32 v104, 0x41e6d4ca, v105
	v_exp_f32_e32 v122, v104
	v_min_f32_e32 v104, 0x41e6d4ca, v106
	v_exp_f32_e32 v105, v104
	v_min_f32_e32 v104, 0x41e6d4ca, v107
	v_exp_f32_e32 v104, v104
	v_pk_mul_f32 v[106:107], v[118:119], v[124:125] op_sel_hi:[1,0]
	v_pk_add_f32 v[118:119], v[122:123], 1.0 op_sel_hi:[1,0]
	v_pk_mul_f32 v[48:49], v[48:49], v[200:201]
	v_pk_add_f32 v[104:105], v[104:105], 1.0 op_sel_hi:[1,0]
	v_mul_f32_e32 v122, v119, v118
	v_mul_f32_e32 v123, v105, v104
	v_pk_mul_f32 v[40:41], v[40:41], v[200:201]
	v_mul_f32_e32 v124, v122, v123
	v_rcp_f32_e32 v125, v124
	v_pk_mul_f32 v[106:107], v[52:53], v[106:107]
	v_add_u32_e32 v126, 0x80, v197
	v_pk_mul_f32 v[106:107], v[48:49], v[106:107]
	v_mul_f32_e32 v124, v123, v125
	v_mul_f32_e32 v122, v122, v125
	v_pk_mul_f32 v[118:119], v[118:119], v[124:125] op_sel_hi:[1,0]
	v_pk_mul_f32 v[104:105], v[104:105], v[122:123] op_sel_hi:[1,0]
	v_pk_mul_f32 v[118:119], v[44:45], v[118:119]
	v_pk_mul_f32 v[104:105], v[46:47], v[104:105]
	v_pk_mul_f32 v[118:119], v[40:41], v[118:119]
	v_pk_mul_f32 v[120:121], v[54:55], v[120:121]
	v_pk_mul_f32 v[122:123], v[42:43], v[104:105]
	v_cvt_pk_bf16_f32 v104, v106, v107
	v_cvt_pk_bf16_f32 v106, v118, v119
	v_mov_b64_e32 v[118:119], s[86:87]
	v_pk_mul_f32 v[120:121], v[50:51], v[120:121]
	v_mad_i64_i32 v[118:119], s[10:11], v126, s90, v[118:119]
	v_cvt_pk_bf16_f32 v105, v120, v121
	v_cvt_pk_bf16_f32 v107, v122, v123
	v_lshl_add_u64 v[118:119], v[192:193], 1, v[118:119]
	global_store_dwordx4 v[118:119], v[104:107], off
	s_and_saveexec_b64 s[10:11], s[42:43]
	s_cbranch_execz .LBB0_782
	s_add_u32 s24, s4, s15
	s_addc_u32 s25, s5, s16
	v_lshl_add_u64 v[104:105], v[192:193], 2, s[24:25]
	global_store_dwordx4 v[104:105], v[52:55], off
	s_nop 1
	v_add_co_u32_e32 v52, vcc, 0x2000, v104
	s_nop 1
	v_addc_co_u32_e32 v53, vcc, 0, v105, vcc
	v_add_co_u32_e32 v54, vcc, 0x5000, v104
	global_store_dwordx4 v[52:53], v[92:95], off offset:3072
	s_nop 0
	v_addc_co_u32_e32 v55, vcc, 0, v105, vcc
	global_store_dwordx4 v[54:55], v[48:51], off offset:2048
	global_store_dwordx4 v[104:105], v[44:47], off offset:16
	global_store_dwordx4 v[52:53], v[88:91], off offset:3088
	global_store_dwordx4 v[54:55], v[40:43], off offset:2064
.LBB0_782:
	s_or_b64 exec, exec, s[10:11]
	s_nop 0
	v_mov_b32_e32 v40, v198
	v_mov_b32_e32 v41, v198
	v_pk_mul_f32 v[44:45], v[22:23], v[40:41]
	v_pk_mul_f32 v[40:41], v[18:19], v[40:41]
	v_pk_mul_f32 v[18:19], v[24:25], v[196:197] op_sel_hi:[1,0]
	v_mov_b32_e32 v24, v194
	v_mov_b32_e32 v25, v194
	v_pk_mul_f32 v[6:7], v[6:7], v[24:25]
	v_pk_mul_f32 v[2:3], v[2:3], v[24:25]
	v_mov_b32_e32 v24, 0
	v_mov_b32_e32 v25, 0
	v_mov_b32_e32 v199, v198
	v_mov_b32_dpp v24, v92 row_ror:1 row_mask:0xf bank_mask:0xf
	v_mov_b32_dpp v25, v93 row_ror:1 row_mask:0xf bank_mask:0xf
	v_pk_mul_f32 v[42:43], v[16:17], v[198:199]
	v_pk_mul_f32 v[22:23], v[28:29], v[196:197] op_sel_hi:[1,0]
	v_pk_mul_f32 v[16:17], v[26:27], v[196:197] op_sel_hi:[1,0]
	v_mov_b64_e32 v[26:27], 0
	v_mov_b64_e32 v[28:29], 0
	v_mov_b32_dpp v24, v116 row_shr:1 row_mask:0xf bank_mask:0xf
	v_mov_b32_dpp v25, v117 row_shr:1 row_mask:0xf bank_mask:0xf
	v_mov_b32_dpp v26, v94 row_ror:1 row_mask:0xf bank_mask:0xf
	v_mov_b32_dpp v27, v95 row_ror:1 row_mask:0xf bank_mask:0xf
	v_mov_b32_dpp v28, v22 row_ror:15 row_mask:0xf bank_mask:0xf
	v_mov_b32_dpp v29, v23 row_ror:15 row_mask:0xf bank_mask:0xf
	v_pk_fma_f32 v[24:25], v[80:81], v[24:25], v[84:85]
	v_pk_mul_f32 v[46:47], v[20:21], v[198:199]
	v_pk_mul_f32 v[20:21], v[30:31], v[196:197] op_sel_hi:[1,0]
	v_mov_b64_e32 v[30:31], 0
	v_mov_b32_dpp v26, v114 row_shr:1 row_mask:0xf bank_mask:0xf
	v_mov_b32_dpp v27, v115 row_shr:1 row_mask:0xf bank_mask:0xf
	v_mov_b32_dpp v28, v116 row_shl:1 row_mask:0xf bank_mask:0xf
	v_mov_b32_dpp v29, v117 row_shl:1 row_mask:0xf bank_mask:0xf
	v_pk_fma_f32 v[24:25], v[116:117], v[76:77], v[24:25]
	v_mov_b32_dpp v30, v20 row_ror:15 row_mask:0xf bank_mask:0xf
	v_mov_b32_dpp v31, v21 row_ror:15 row_mask:0xf bank_mask:0xf
	v_pk_fma_f32 v[26:27], v[82:83], v[26:27], v[86:87]
	v_pk_fma_f32 v[24:25], v[72:73], v[28:29], v[24:25]
	v_mov_b32_dpp v30, v114 row_shl:1 row_mask:0xf bank_mask:0xf
	v_mov_b32_dpp v31, v115 row_shl:1 row_mask:0xf bank_mask:0xf
	v_pk_fma_f32 v[26:27], v[114:115], v[78:79], v[26:27]
	v_pk_mul_f32 v[28:29], v[24:25], v[24:25]
	v_pk_fma_f32 v[26:27], v[74:75], v[30:31], v[26:27]
	v_pk_mul_f32 v[28:29], v[24:25], v[28:29]
	v_pk_mul_f32 v[30:31], v[26:27], v[26:27]
	v_pk_fma_f32 v[28:29], v[28:29], s[70:71], v[24:25] op_sel_hi:[1,0,1]
	v_pk_mul_f32 v[30:31], v[26:27], v[30:31]
	v_pk_mul_f32 v[28:29], v[28:29], s[72:73] op_sel_hi:[1,0]
	v_pk_fma_f32 v[30:31], v[30:31], s[70:71], v[26:27] op_sel_hi:[1,0,1]
	v_min_f32_e32 v28, 0x41e6d4ca, v28
	v_pk_mul_f32 v[30:31], v[30:31], s[72:73] op_sel_hi:[1,0]
	v_exp_f32_e32 v49, v28
	v_min_f32_e32 v28, 0x41e6d4ca, v29
	v_exp_f32_e32 v48, v28
	v_min_f32_e32 v28, 0x41e6d4ca, v30
	v_exp_f32_e32 v29, v28
	v_min_f32_e32 v28, 0x41e6d4ca, v31
	v_exp_f32_e32 v28, v28
	v_pk_add_f32 v[30:31], v[48:49], 1.0 op_sel_hi:[1,0]
	v_add_u32_e32 v52, 0x90, v197
	v_pk_add_f32 v[28:29], v[28:29], 1.0 op_sel_hi:[1,0]
	v_mul_f32_e32 v48, v31, v30
	v_mul_f32_e32 v49, v29, v28
	v_pk_mul_f32 v[12:13], v[12:13], v[196:197] op_sel_hi:[1,0]
	v_mul_f32_e32 v50, v48, v49
	v_rcp_f32_e32 v51, v50
	v_pk_mul_f32 v[14:15], v[14:15], v[196:197] op_sel_hi:[1,0]
	v_pk_mul_f32 v[10:11], v[10:11], v[196:197] op_sel_hi:[1,0]
	v_pk_mul_f32 v[8:9], v[8:9], v[196:197] op_sel_hi:[1,0]
	v_mul_f32_e32 v48, v48, v51
	v_pk_mul_f32 v[28:29], v[28:29], v[48:49] op_sel_hi:[1,0]
	v_mul_f32_e32 v50, v49, v51
	v_pk_mul_f32 v[26:27], v[26:27], v[28:29]
	v_pk_mul_f32 v[30:31], v[30:31], v[50:51] op_sel_hi:[1,0]
	v_pk_mul_f32 v[28:29], v[44:45], v[26:27]
	v_mov_b32_e32 v26, 0
	v_mov_b32_e32 v27, 0
	v_pk_mul_f32 v[24:25], v[24:25], v[30:31]
	v_mov_b32_dpp v26, v88 row_ror:1 row_mask:0xf bank_mask:0xf
	v_mov_b32_dpp v27, v89 row_ror:1 row_mask:0xf bank_mask:0xf
	v_mov_b64_e32 v[30:31], 0
	v_mov_b64_e32 v[44:45], 0
	v_mov_b32_dpp v26, v110 row_shr:1 row_mask:0xf bank_mask:0xf
	v_mov_b32_dpp v27, v111 row_shr:1 row_mask:0xf bank_mask:0xf
	v_mov_b32_dpp v30, v90 row_ror:1 row_mask:0xf bank_mask:0xf
	v_mov_b32_dpp v31, v91 row_ror:1 row_mask:0xf bank_mask:0xf
	v_mov_b32_dpp v44, v18 row_ror:15 row_mask:0xf bank_mask:0xf
	v_mov_b32_dpp v45, v19 row_ror:15 row_mask:0xf bank_mask:0xf
	v_pk_fma_f32 v[26:27], v[64:65], v[26:27], v[68:69]
	v_pk_mul_f32 v[24:25], v[46:47], v[24:25]
	v_mov_b64_e32 v[46:47], 0
	v_mov_b32_dpp v30, v108 row_shr:1 row_mask:0xf bank_mask:0xf
	v_mov_b32_dpp v31, v109 row_shr:1 row_mask:0xf bank_mask:0xf
	v_mov_b32_dpp v44, v110 row_shl:1 row_mask:0xf bank_mask:0xf
	v_mov_b32_dpp v45, v111 row_shl:1 row_mask:0xf bank_mask:0xf
	v_pk_fma_f32 v[26:27], v[110:111], v[60:61], v[26:27]
	v_mov_b32_dpp v46, v16 row_ror:15 row_mask:0xf bank_mask:0xf
	v_mov_b32_dpp v47, v17 row_ror:15 row_mask:0xf bank_mask:0xf
	v_pk_fma_f32 v[30:31], v[66:67], v[30:31], v[70:71]
	v_pk_fma_f32 v[26:27], v[56:57], v[44:45], v[26:27]
	v_mov_b32_dpp v46, v108 row_shl:1 row_mask:0xf bank_mask:0xf
	v_mov_b32_dpp v47, v109 row_shl:1 row_mask:0xf bank_mask:0xf
	v_pk_fma_f32 v[30:31], v[108:109], v[62:63], v[30:31]
	v_pk_mul_f32 v[44:45], v[26:27], v[26:27]
	v_pk_fma_f32 v[30:31], v[58:59], v[46:47], v[30:31]
	v_pk_mul_f32 v[44:45], v[26:27], v[44:45]
	v_pk_mul_f32 v[46:47], v[30:31], v[30:31]
	v_pk_fma_f32 v[44:45], v[44:45], s[70:71], v[26:27] op_sel_hi:[1,0,1]
	v_pk_mul_f32 v[46:47], v[30:31], v[46:47]
	v_pk_mul_f32 v[44:45], v[44:45], s[72:73] op_sel_hi:[1,0]
	v_pk_fma_f32 v[46:47], v[46:47], s[70:71], v[30:31] op_sel_hi:[1,0,1]
	v_min_f32_e32 v44, 0x41e6d4ca, v44
	v_pk_mul_f32 v[46:47], v[46:47], s[72:73] op_sel_hi:[1,0]
	v_exp_f32_e32 v49, v44
	v_min_f32_e32 v44, 0x41e6d4ca, v45
	v_exp_f32_e32 v48, v44
	v_min_f32_e32 v44, 0x41e6d4ca, v46
	v_exp_f32_e32 v45, v44
	v_min_f32_e32 v44, 0x41e6d4ca, v47
	v_exp_f32_e32 v44, v44
	v_pk_add_f32 v[46:47], v[48:49], 1.0 op_sel_hi:[1,0]
	v_mov_b32_dpp v100, v36 row_shl:1 row_mask:0xf bank_mask:0xf
	v_pk_add_f32 v[44:45], v[44:45], 1.0 op_sel_hi:[1,0]
	v_mul_f32_e32 v48, v47, v46
	v_mul_f32_e32 v49, v45, v44
	v_mov_b32_dpp v101, v37 row_shl:1 row_mask:0xf bank_mask:0xf
	v_mul_f32_e32 v50, v48, v49
	v_rcp_f32_e32 v51, v50
	v_mov_b32_dpp v102, v38 row_shl:1 row_mask:0xf bank_mask:0xf
	v_mov_b32_dpp v103, v39 row_shl:1 row_mask:0xf bank_mask:0xf
	v_pk_mul_f32 v[4:5], v[4:5], v[194:195]
	v_mul_f32_e32 v50, v49, v51
	v_mul_f32_e32 v48, v48, v51
	v_pk_mul_f32 v[44:45], v[44:45], v[48:49] op_sel_hi:[1,0]
	v_pk_mul_f32 v[46:47], v[46:47], v[50:51] op_sel_hi:[1,0]
	v_pk_mul_f32 v[30:31], v[30:31], v[44:45]
	v_pk_mul_f32 v[26:27], v[26:27], v[46:47]
	v_pk_mul_f32 v[30:31], v[40:41], v[30:31]
	v_pk_mul_f32 v[40:41], v[42:43], v[26:27]
	v_cvt_pk_bf16_f32 v26, v24, v25
	v_mov_b64_e32 v[24:25], s[86:87]
	v_cvt_pk_bf16_f32 v27, v28, v29
	v_cvt_pk_bf16_f32 v29, v30, v31
	v_mad_i64_i32 v[30:31], s[10:11], v52, s90, v[24:25]
	v_cvt_pk_bf16_f32 v28, v40, v41
	v_lshl_add_u64 v[30:31], v[30:31], 0, v[112:113]
	global_store_dwordx4 v[30:31], v[26:29], off
	v_mov_b64_e32 v[30:31], 0
	v_mov_b32_e32 v26, 0
	v_mov_b32_e32 v27, 0
	v_mov_b32_e32 v28, 0
	v_mov_b32_dpp v26, v116 row_ror:1 row_mask:0xf bank_mask:0xf
	v_mov_b32_dpp v27, v117 row_ror:1 row_mask:0xf bank_mask:0xf
	v_mov_b32_e32 v29, 0
	v_mov_b32_dpp v26, v22 row_shr:1 row_mask:0xf bank_mask:0xf
	v_mov_b32_dpp v27, v23 row_shr:1 row_mask:0xf bank_mask:0xf
	v_mov_b32_dpp v28, v114 row_ror:1 row_mask:0xf bank_mask:0xf
	v_mov_b32_dpp v29, v115 row_ror:1 row_mask:0xf bank_mask:0xf
	v_mov_b32_dpp v30, v36 row_ror:15 row_mask:0xf bank_mask:0xf
	v_mov_b32_dpp v31, v37 row_ror:15 row_mask:0xf bank_mask:0xf
	v_pk_fma_f32 v[26:27], v[80:81], v[26:27], v[84:85]
	v_mov_b64_e32 v[40:41], 0
	v_mov_b32_dpp v28, v20 row_shr:1 row_mask:0xf bank_mask:0xf
	v_mov_b32_dpp v29, v21 row_shr:1 row_mask:0xf bank_mask:0xf
	v_mov_b32_dpp v30, v22 row_shl:1 row_mask:0xf bank_mask:0xf
	v_mov_b32_dpp v31, v23 row_shl:1 row_mask:0xf bank_mask:0xf
	v_pk_fma_f32 v[26:27], v[22:23], v[76:77], v[26:27]
	v_mov_b32_dpp v40, v38 row_ror:15 row_mask:0xf bank_mask:0xf
	v_mov_b32_dpp v41, v39 row_ror:15 row_mask:0xf bank_mask:0xf
	v_pk_fma_f32 v[28:29], v[82:83], v[28:29], v[86:87]
	v_pk_fma_f32 v[26:27], v[72:73], v[30:31], v[26:27]
	v_mov_b32_dpp v40, v20 row_shl:1 row_mask:0xf bank_mask:0xf
	v_mov_b32_dpp v41, v21 row_shl:1 row_mask:0xf bank_mask:0xf
	v_pk_fma_f32 v[28:29], v[20:21], v[78:79], v[28:29]
	v_pk_mul_f32 v[30:31], v[26:27], v[26:27]
	v_pk_fma_f32 v[28:29], v[74:75], v[40:41], v[28:29]
	v_pk_mul_f32 v[30:31], v[26:27], v[30:31]
	v_pk_mul_f32 v[40:41], v[28:29], v[28:29]
	v_pk_fma_f32 v[30:31], v[30:31], s[70:71], v[26:27] op_sel_hi:[1,0,1]
	v_pk_mul_f32 v[40:41], v[28:29], v[40:41]
	v_pk_mul_f32 v[30:31], v[30:31], s[72:73] op_sel_hi:[1,0]
	v_pk_fma_f32 v[40:41], v[40:41], s[70:71], v[28:29] op_sel_hi:[1,0,1]
	v_min_f32_e32 v30, 0x41e6d4ca, v30
	v_pk_mul_f32 v[40:41], v[40:41], s[72:73] op_sel_hi:[1,0]
	v_exp_f32_e32 v43, v30
	v_min_f32_e32 v30, 0x41e6d4ca, v31
	v_exp_f32_e32 v42, v30
	v_min_f32_e32 v30, 0x41e6d4ca, v40
	v_exp_f32_e32 v31, v30
	v_min_f32_e32 v30, 0x41e6d4ca, v41
	v_exp_f32_e32 v30, v30
	v_pk_add_f32 v[40:41], v[42:43], 1.0 op_sel_hi:[1,0]
	v_add_u32_e32 v46, 0xa0, v197
	v_pk_add_f32 v[30:31], v[30:31], 1.0 op_sel_hi:[1,0]
	v_mul_f32_e32 v42, v41, v40
	v_mul_f32_e32 v43, v31, v30
	v_mov_b32_dpp v96, v32 row_shl:1 row_mask:0xf bank_mask:0xf
	v_mul_f32_e32 v44, v42, v43
	v_rcp_f32_e32 v45, v44
	v_mov_b32_dpp v97, v33 row_shl:1 row_mask:0xf bank_mask:0xf
	v_mov_b32_dpp v98, v34 row_shl:1 row_mask:0xf bank_mask:0xf
	v_mov_b32_dpp v99, v35 row_shl:1 row_mask:0xf bank_mask:0xf
	v_mul_f32_e32 v44, v43, v45
	v_pk_mul_f32 v[40:41], v[40:41], v[44:45] op_sel_hi:[1,0]
	v_mul_f32_e32 v42, v42, v45
	v_pk_mul_f32 v[26:27], v[26:27], v[40:41]
	v_pk_mul_f32 v[30:31], v[30:31], v[42:43] op_sel_hi:[1,0]
	v_pk_mul_f32 v[12:13], v[12:13], v[26:27]
	v_mov_b32_e32 v26, 0
	v_mov_b32_e32 v27, 0
	v_pk_mul_f32 v[28:29], v[28:29], v[30:31]
	v_mov_b32_dpp v26, v110 row_ror:1 row_mask:0xf bank_mask:0xf
	v_mov_b32_dpp v27, v111 row_ror:1 row_mask:0xf bank_mask:0xf
	v_pk_mul_f32 v[14:15], v[14:15], v[28:29]
	v_mov_b64_e32 v[28:29], 0
	v_mov_b64_e32 v[30:31], 0
	v_mov_b32_dpp v26, v18 row_shr:1 row_mask:0xf bank_mask:0xf
	v_mov_b32_dpp v27, v19 row_shr:1 row_mask:0xf bank_mask:0xf
	v_mov_b32_dpp v28, v108 row_ror:1 row_mask:0xf bank_mask:0xf
	v_mov_b32_dpp v29, v109 row_ror:1 row_mask:0xf bank_mask:0xf
	v_mov_b32_dpp v30, v32 row_ror:15 row_mask:0xf bank_mask:0xf
	v_mov_b32_dpp v31, v33 row_ror:15 row_mask:0xf bank_mask:0xf
	v_pk_fma_f32 v[26:27], v[64:65], v[26:27], v[68:69]
	v_mov_b64_e32 v[40:41], 0
	v_mov_b32_dpp v28, v16 row_shr:1 row_mask:0xf bank_mask:0xf
	v_mov_b32_dpp v29, v17 row_shr:1 row_mask:0xf bank_mask:0xf
	v_mov_b32_dpp v30, v18 row_shl:1 row_mask:0xf bank_mask:0xf
	v_mov_b32_dpp v31, v19 row_shl:1 row_mask:0xf bank_mask:0xf
	v_pk_fma_f32 v[26:27], v[18:19], v[60:61], v[26:27]
	v_mov_b32_dpp v40, v34 row_ror:15 row_mask:0xf bank_mask:0xf
	v_mov_b32_dpp v41, v35 row_ror:15 row_mask:0xf bank_mask:0xf
	v_pk_fma_f32 v[28:29], v[66:67], v[28:29], v[70:71]
	v_pk_fma_f32 v[26:27], v[56:57], v[30:31], v[26:27]
	v_mov_b32_dpp v40, v16 row_shl:1 row_mask:0xf bank_mask:0xf
	v_mov_b32_dpp v41, v17 row_shl:1 row_mask:0xf bank_mask:0xf
	v_pk_fma_f32 v[28:29], v[16:17], v[62:63], v[28:29]
	v_pk_mul_f32 v[30:31], v[26:27], v[26:27]
	v_pk_fma_f32 v[28:29], v[58:59], v[40:41], v[28:29]
	v_pk_mul_f32 v[30:31], v[26:27], v[30:31]
	v_pk_mul_f32 v[40:41], v[28:29], v[28:29]
	v_pk_fma_f32 v[30:31], v[30:31], s[70:71], v[26:27] op_sel_hi:[1,0,1]
	v_pk_mul_f32 v[40:41], v[28:29], v[40:41]
	v_pk_mul_f32 v[30:31], v[30:31], s[72:73] op_sel_hi:[1,0]
	v_pk_fma_f32 v[40:41], v[40:41], s[70:71], v[28:29] op_sel_hi:[1,0,1]
	v_min_f32_e32 v30, 0x41e6d4ca, v30
	v_pk_mul_f32 v[40:41], v[40:41], s[72:73] op_sel_hi:[1,0]
	v_exp_f32_e32 v43, v30
	v_min_f32_e32 v30, 0x41e6d4ca, v31
	v_exp_f32_e32 v42, v30
	v_min_f32_e32 v30, 0x41e6d4ca, v40
	v_exp_f32_e32 v31, v30
	v_min_f32_e32 v30, 0x41e6d4ca, v41
	v_exp_f32_e32 v30, v30
	v_pk_add_f32 v[40:41], v[42:43], 1.0 op_sel_hi:[1,0]
	v_pk_mul_f32 v[0:1], v[0:1], v[194:195]
	v_pk_add_f32 v[30:31], v[30:31], 1.0 op_sel_hi:[1,0]
	v_mul_f32_e32 v42, v41, v40
	v_mul_f32_e32 v43, v31, v30
	s_nop 0
	v_mul_f32_e32 v44, v42, v43
	v_rcp_f32_e32 v45, v44
	s_nop 0
	v_mul_f32_e32 v44, v43, v45
	v_mul_f32_e32 v42, v42, v45
	v_pk_mul_f32 v[30:31], v[30:31], v[42:43] op_sel_hi:[1,0]
	v_pk_mul_f32 v[40:41], v[40:41], v[44:45] op_sel_hi:[1,0]
	v_pk_mul_f32 v[28:29], v[28:29], v[30:31]
	v_pk_mul_f32 v[26:27], v[26:27], v[40:41]
	v_pk_mul_f32 v[28:29], v[10:11], v[28:29]
	v_pk_mul_f32 v[10:11], v[8:9], v[26:27]
	v_cvt_pk_bf16_f32 v8, v12, v13
	v_mad_i64_i32 v[12:13], s[10:11], v46, s90, v[24:25]
	v_cvt_pk_bf16_f32 v9, v14, v15
	v_cvt_pk_bf16_f32 v10, v10, v11
	v_cvt_pk_bf16_f32 v11, v28, v29
	v_lshl_add_u64 v[12:13], v[12:13], 0, v[112:113]
	global_store_dwordx4 v[12:13], v[8:11], off
	v_add_u32_e32 v30, 0xb0, v197
	s_nop 0
	v_mov_b32_e32 v8, 0
	v_mov_b32_e32 v9, 0
	v_mov_b32_e32 v10, 0
	v_mov_b32_dpp v8, v22 row_ror:1 row_mask:0xf bank_mask:0xf
	v_mov_b32_dpp v9, v23 row_ror:1 row_mask:0xf bank_mask:0xf
	v_mov_b32_e32 v11, 0
	v_mov_b32_dpp v8, v36 row_shr:1 row_mask:0xf bank_mask:0xf
	v_mov_b32_dpp v9, v37 row_shr:1 row_mask:0xf bank_mask:0xf
	v_mov_b32_dpp v10, v20 row_ror:1 row_mask:0xf bank_mask:0xf
	v_mov_b32_dpp v11, v21 row_ror:1 row_mask:0xf bank_mask:0xf
	v_pk_fma_f32 v[8:9], v[80:81], v[8:9], v[84:85]
	v_mov_b32_dpp v10, v38 row_shr:1 row_mask:0xf bank_mask:0xf
	v_mov_b32_dpp v11, v39 row_shr:1 row_mask:0xf bank_mask:0xf
	v_pk_fma_f32 v[8:9], v[36:37], v[76:77], v[8:9]
	v_pk_fma_f32 v[10:11], v[82:83], v[10:11], v[86:87]
	v_pk_fma_f32 v[8:9], v[72:73], v[100:101], v[8:9]
	v_pk_fma_f32 v[10:11], v[38:39], v[78:79], v[10:11]
	v_pk_mul_f32 v[12:13], v[8:9], v[8:9]
	v_pk_fma_f32 v[10:11], v[74:75], v[102:103], v[10:11]
	v_pk_mul_f32 v[12:13], v[8:9], v[12:13]
	v_pk_mul_f32 v[14:15], v[10:11], v[10:11]
	v_pk_fma_f32 v[12:13], v[12:13], s[70:71], v[8:9] op_sel_hi:[1,0,1]
	v_pk_mul_f32 v[14:15], v[10:11], v[14:15]
	v_pk_mul_f32 v[12:13], v[12:13], s[72:73] op_sel_hi:[1,0]
	v_pk_fma_f32 v[14:15], v[14:15], s[70:71], v[10:11] op_sel_hi:[1,0,1]
	v_min_f32_e32 v12, 0x41e6d4ca, v12
	v_pk_mul_f32 v[14:15], v[14:15], s[72:73] op_sel_hi:[1,0]
	v_exp_f32_e32 v21, v12
	v_min_f32_e32 v12, 0x41e6d4ca, v13
	v_exp_f32_e32 v20, v12
	v_min_f32_e32 v12, 0x41e6d4ca, v14
	v_exp_f32_e32 v13, v12
	v_min_f32_e32 v12, 0x41e6d4ca, v15
	v_exp_f32_e32 v12, v12
	v_pk_add_f32 v[14:15], v[20:21], 1.0 op_sel_hi:[1,0]
	v_pk_add_f32 v[12:13], v[12:13], 1.0 op_sel_hi:[1,0]
	v_mul_f32_e32 v20, v15, v14
	v_mul_f32_e32 v21, v13, v12
	s_nop 0
	v_mul_f32_e32 v22, v20, v21
	v_rcp_f32_e32 v23, v22
	s_nop 0
	v_mul_f32_e32 v20, v20, v23
	v_pk_mul_f32 v[12:13], v[12:13], v[20:21] op_sel_hi:[1,0]
	v_mul_f32_e32 v22, v21, v23
	v_pk_mul_f32 v[12:13], v[10:11], v[12:13]
	v_pk_mul_f32 v[14:15], v[14:15], v[22:23] op_sel_hi:[1,0]
	v_pk_mul_f32 v[20:21], v[6:7], v[12:13]
	v_mov_b32_e32 v12, 0
	v_mov_b32_e32 v13, 0
	v_pk_mul_f32 v[14:15], v[8:9], v[14:15]
	v_mov_b32_dpp v12, v18 row_ror:1 row_mask:0xf bank_mask:0xf
	v_mov_b32_dpp v13, v19 row_ror:1 row_mask:0xf bank_mask:0xf
	v_pk_mul_f32 v[22:23], v[4:5], v[14:15]
	v_mov_b32_e32 v14, 0
	v_mov_b32_e32 v15, 0
	v_mov_b32_dpp v12, v32 row_shr:1 row_mask:0xf bank_mask:0xf
	v_mov_b32_dpp v13, v33 row_shr:1 row_mask:0xf bank_mask:0xf
	v_mov_b32_dpp v14, v16 row_ror:1 row_mask:0xf bank_mask:0xf
	v_mov_b32_dpp v15, v17 row_ror:1 row_mask:0xf bank_mask:0xf
	v_pk_fma_f32 v[12:13], v[64:65], v[12:13], v[68:69]
	v_mov_b32_dpp v14, v34 row_shr:1 row_mask:0xf bank_mask:0xf
	v_mov_b32_dpp v15, v35 row_shr:1 row_mask:0xf bank_mask:0xf
	v_pk_fma_f32 v[12:13], v[32:33], v[60:61], v[12:13]
	v_pk_fma_f32 v[14:15], v[66:67], v[14:15], v[70:71]
	v_pk_fma_f32 v[12:13], v[56:57], v[96:97], v[12:13]
	v_pk_fma_f32 v[14:15], v[34:35], v[62:63], v[14:15]
	v_pk_mul_f32 v[16:17], v[12:13], v[12:13]
	v_pk_fma_f32 v[14:15], v[58:59], v[98:99], v[14:15]
	v_pk_mul_f32 v[16:17], v[12:13], v[16:17]
	v_pk_mul_f32 v[18:19], v[14:15], v[14:15]
	v_pk_fma_f32 v[16:17], v[16:17], s[70:71], v[12:13] op_sel_hi:[1,0,1]
	v_pk_mul_f32 v[18:19], v[14:15], v[18:19]
	v_pk_mul_f32 v[16:17], v[16:17], s[72:73] op_sel_hi:[1,0]
	v_pk_fma_f32 v[18:19], v[18:19], s[70:71], v[14:15] op_sel_hi:[1,0,1]
	v_min_f32_e32 v16, 0x41e6d4ca, v16
	v_pk_mul_f32 v[18:19], v[18:19], s[72:73] op_sel_hi:[1,0]
	v_exp_f32_e32 v27, v16
	v_min_f32_e32 v16, 0x41e6d4ca, v17
	v_exp_f32_e32 v26, v16
	v_min_f32_e32 v16, 0x41e6d4ca, v18
	v_exp_f32_e32 v17, v16
	v_min_f32_e32 v16, 0x41e6d4ca, v19
	v_exp_f32_e32 v16, v16
	v_pk_add_f32 v[18:19], v[26:27], 1.0 op_sel_hi:[1,0]
	v_pk_add_f32 v[16:17], v[16:17], 1.0 op_sel_hi:[1,0]
	v_mul_f32_e32 v26, v19, v18
	v_mul_f32_e32 v27, v17, v16
	s_nop 0
	v_mul_f32_e32 v28, v26, v27
	v_rcp_f32_e32 v29, v28
	s_nop 0
	v_mul_f32_e32 v28, v27, v29
	v_mul_f32_e32 v26, v26, v29
	v_pk_mul_f32 v[16:17], v[16:17], v[26:27] op_sel_hi:[1,0]
	v_pk_mul_f32 v[18:19], v[18:19], v[28:29] op_sel_hi:[1,0]
	v_pk_mul_f32 v[16:17], v[14:15], v[16:17]
	v_pk_mul_f32 v[18:19], v[12:13], v[18:19]
	v_pk_mul_f32 v[26:27], v[2:3], v[16:17]
	v_pk_mul_f32 v[18:19], v[0:1], v[18:19]
	v_cvt_pk_bf16_f32 v17, v20, v21
	v_mad_i64_i32 v[20:21], s[10:11], v30, s90, v[24:25]
	v_cvt_pk_bf16_f32 v16, v22, v23
	v_cvt_pk_bf16_f32 v18, v18, v19
	v_cvt_pk_bf16_f32 v19, v26, v27
	v_lshl_add_u64 v[20:21], v[20:21], 0, v[112:113]
	global_store_dwordx4 v[20:21], v[16:19], off
	s_and_saveexec_b64 s[10:11], s[64:65]
	s_cbranch_execz .LBB0_784
	s_add_u32 s14, s4, s14
	s_addc_u32 s15, s5, s12
	v_lshl_add_u64 v[16:17], v[192:193], 2, s[14:15]
	global_store_dwordx4 v[16:17], v[8:11], off
	s_nop 1
	v_add_co_u32_e32 v8, vcc, 0x2000, v16
	s_nop 1
	v_addc_co_u32_e32 v9, vcc, 0, v17, vcc
	v_add_co_u32_e32 v10, vcc, 0x5000, v16
	global_store_dwordx4 v[8:9], v[36:39], off offset:3072
	s_nop 0
	v_addc_co_u32_e32 v11, vcc, 0, v17, vcc
	global_store_dwordx4 v[10:11], v[4:7], off offset:2048
	global_store_dwordx4 v[16:17], v[12:15], off offset:16
	global_store_dwordx4 v[8:9], v[32:35], off offset:3088
	global_store_dwordx4 v[10:11], v[0:3], off offset:2064
